# retention path of the chunk-output phase: dead conv-neighbour zero-inits and the early load drain removed
# baseline (speedup 1.0000x reference)
.LBB0_507:
	s_mov_b64 s[6:7], 0x200
.LBB0_508:
	s_lshl_b32 s68, s6, 1
	v_lshl_add_u64 v[2:3], v[0:1], 0, s[68:69]
	s_and_b64 vcc, exec, s[12:13]
	s_cbranch_vccz .Lkc5_ld
	s_lshl_b32 s68, s39, 3
	s_or_b32 s68, s68, s42
	s_mul_i32 s68, s68, 0x42
	s_add_i32 s68, s68, s38
	s_lshl_b32 s68, s68, 14
	s_add_i32 s68, s68, 0x2100000
	v_lshlrev_b32_e32 v4, 7, v248
	v_lshl_add_u32 v4, v251, 6, v4
	v_add_u32_e32 v4, s68, v4
	v_mov_b32_e32 v5, 0
	v_lshl_add_u64 v[2:3], s[44:45], 0, v[4:5]
